# stack of load-batching edits on v11: S_raw fragment loads, conv_b row loads, sample-item prologue loads (checking for a gain outside noise)
# speedup vs baseline: 1.0808x; 1.0001x over previous
.LBB0_586:
	s_or_b64 exec, exec, s[6:7]
	v_lshlrev_b32_e32 v32, 1, v34
	v_ashrrev_i32_e32 v39, 31, v38
	v_lshl_add_u64 v[22:23], s[18:19], 0, v[32:33]
	v_lshlrev_b64 v[44:45], 12, v[38:39]
	v_lshl_add_u64 v[26:27], v[22:23], 0, v[44:45]
	flat_load_dwordx2 v[48:49], v[26:27]
	s_mov_b32 s60, 0x1000
	s_mov_b32 s61, 0
	v_lshl_add_u64 v[82:83], v[26:27], 0, s[60:61]
	global_load_dwordx2 v[84:85], v[82:83], off
	v_lshl_add_u64 v[82:83], v[82:83], 0, s[60:61]
	global_load_dwordx2 v[86:87], v[82:83], off
	v_lshl_add_u64 v[82:83], v[82:83], 0, s[60:61]
	global_load_dwordx2 v[88:89], v[82:83], off
	v_lshl_add_u64 v[82:83], v[82:83], 0, s[60:61]
	global_load_dwordx2 v[90:91], v[82:83], off
	v_lshl_add_u64 v[82:83], v[82:83], 0, s[60:61]
	global_load_dwordx2 v[92:93], v[82:83], off
	v_lshl_add_u64 v[82:83], v[82:83], 0, s[60:61]
	global_load_dwordx2 v[94:95], v[82:83], off
	v_lshl_add_u64 v[82:83], v[82:83], 0, s[60:61]
	global_load_dwordx2 v[96:97], v[82:83], off
	s_waitcnt vmcnt(0) lgkmcnt(0)
	v_mov_b32_e32 v26, v4
	v_pk_fma_f32 v[46:47], v[6:7], v[30:31], v[2:3]
	v_pk_fma_f32 v[50:51], v[4:5], v[28:29], v[0:1]
	v_or_b32_e32 v4, 1, v38
	v_mov_b32_e32 v27, v6
	v_mov_b32_e32 v28, v8
	v_mov_b32_e32 v29, v10
	v_mov_b32_e32 v30, v16
	v_mov_b32_e32 v31, v18
	v_mov_b32_e32 v36, v12
	v_mov_b32_e32 v6, v5
	v_mov_b32_e32 v18, v17
	v_or_b32_e32 v8, 2, v38
	v_or_b32_e32 v12, 3, v38
	v_mov_b32_e32 v16, v50
	v_mov_b32_e32 v17, v46
	v_ashrrev_i32_e32 v5, 31, v4
	v_mov_b32_e32 v37, v14
	v_mov_b32_e32 v10, v9
	v_mov_b32_e32 v14, v13
	v_mov_b32_e32 v46, v51
	v_ashrrev_i32_e32 v9, 31, v8
	v_ashrrev_i32_e32 v13, 31, v12
	v_pk_fma_f32 v[16:17], v[28:29], v[24:25], v[16:17]
	v_lshlrev_b64 v[56:57], 12, v[4:5]
	v_pk_fma_f32 v[50:51], v[10:11], v[42:43], v[46:47]
	v_lshlrev_b64 v[4:5], 12, v[8:9]
	v_lshlrev_b64 v[46:47], 12, v[12:13]
	v_pk_fma_f32 v[8:9], v[30:31], v[20:21], v[16:17]
	v_lshl_add_u64 v[16:17], v[22:23], 0, v[56:57]
	v_pk_fma_f32 v[12:13], v[18:19], v[40:41], v[50:51]
	v_lshl_add_u64 v[58:59], v[22:23], 0, v[4:5]
	v_lshl_add_u64 v[60:61], v[22:23], 0, v[46:47]
	v_mov_b64_e32 v[62:63], v[84:85]
	v_mov_b64_e32 v[64:65], v[86:87]
	v_mov_b64_e32 v[50:51], v[88:89]
	v_mov_b32_e32 v34, v0
	v_mov_b32_e32 v35, v2
	v_add_u32_e32 v52, s0, v52
	v_add_u32_e32 v53, s1, v53
	v_lshlrev_b32_e32 v59, 16, v49
	v_lshlrev_b32_e32 v58, 16, v48
	v_pk_fma_f32 v[8:9], v[36:37], v[58:59], v[8:9]
	v_and_b32_e32 v49, 0xffff0000, v49
	v_and_b32_e32 v48, 0xffff0000, v48
	v_mul_f32_e32 v0, 0xbfb8aa3b, v8
	v_mul_f32_e32 v17, 0xbfb8aa3b, v9
	v_pk_fma_f32 v[12:13], v[14:15], v[48:49], v[12:13]
	v_exp_f32_e32 v16, v0
	v_exp_f32_e32 v17, v17
	v_mul_f32_e32 v2, 0xbfb8aa3b, v12
	v_mul_f32_e32 v39, 0xbfb8aa3b, v13
	v_exp_f32_e32 v60, v2
	v_exp_f32_e32 v61, v39
	v_pk_add_f32 v[16:17], v[16:17], 1.0 op_sel_hi:[1,0]
	v_mov_b32_e32 v2, v1
	v_lshl_add_u64 v[0:1], s[20:21], 0, v[32:33]
	v_div_scale_f32 v32, s[6:7], v16, v16, v8
	v_pk_add_f32 v[60:61], v[60:61], 1.0 op_sel_hi:[1,0]
	v_div_scale_f32 v66, s[6:7], v17, v17, v9
	v_rcp_f32_e32 v71, v32
	v_div_scale_f32 v68, s[8:9], v60, v60, v12
	v_rcp_f32_e32 v72, v66
	v_rcp_f32_e32 v73, v68
	v_fma_f32 v75, -v32, v71, 1.0
	v_div_scale_f32 v39, vcc, v8, v16, v8
	v_fma_f32 v76, -v66, v72, 1.0
	v_fmac_f32_e32 v71, v75, v71
	v_div_scale_f32 v67, s[6:7], v9, v17, v9
	v_fma_f32 v77, -v68, v73, 1.0
	v_fmac_f32_e32 v72, v76, v72
	v_mul_f32_e32 v75, v39, v71
	v_div_scale_f32 v69, s[8:9], v12, v60, v12
	v_fmac_f32_e32 v73, v77, v73
	v_mul_f32_e32 v76, v67, v72
	v_fma_f32 v78, -v32, v75, v39
	v_div_scale_f32 v70, s[26:27], v61, v61, v13
	v_mul_f32_e32 v77, v69, v73
	v_fma_f32 v79, -v66, v76, v67
	v_fmac_f32_e32 v75, v78, v71
	v_rcp_f32_e32 v74, v70
	v_fma_f32 v80, -v68, v77, v69
	v_fmac_f32_e32 v76, v79, v72
	v_fma_f32 v32, -v32, v75, v39
	v_fmac_f32_e32 v77, v80, v73
	v_fma_f32 v39, -v66, v76, v67
	v_div_fmas_f32 v32, v32, v71, v75
	s_mov_b64 vcc, s[6:7]
	v_fma_f32 v66, -v68, v77, v69
	v_div_fixup_f32 v8, v32, v16, v8
	v_div_fmas_f32 v16, v39, v72, v76
	s_mov_b64 vcc, s[8:9]
	v_div_fixup_f32 v9, v16, v17, v9
	v_div_fmas_f32 v16, v66, v73, v77
	v_div_fixup_f32 v12, v16, v60, v12
	v_fma_f32 v16, -v70, v74, 1.0
	v_fmac_f32_e32 v74, v16, v74
	v_div_scale_f32 v16, vcc, v13, v61, v13
	v_mul_f32_e32 v17, v16, v74
	v_fma_f32 v32, -v70, v17, v16
	v_fmac_f32_e32 v17, v32, v74
	v_fma_f32 v16, -v70, v17, v16
	v_div_fmas_f32 v16, v16, v74, v17
	v_div_fixup_f32 v13, v16, v61, v13
	v_and_b32_sdwa v16, v9, v54 dst_sel:DWORD dst_unused:UNUSED_PAD src0_sel:WORD_1 src1_sel:DWORD
	v_and_b32_sdwa v17, v8, v54 dst_sel:DWORD dst_unused:UNUSED_PAD src0_sel:WORD_1 src1_sel:DWORD
	v_add3_u32 v8, v8, v17, s5
	v_add3_u32 v9, v9, v16, s5
	v_and_b32_sdwa v16, v13, v54 dst_sel:DWORD dst_unused:UNUSED_PAD src0_sel:WORD_1 src1_sel:DWORD
	v_and_b32_sdwa v17, v12, v54 dst_sel:DWORD dst_unused:UNUSED_PAD src0_sel:WORD_1 src1_sel:DWORD
	v_add3_u32 v13, v13, v16, s5
	v_add3_u32 v12, v12, v17, s5
	v_and_b32_e32 v13, 0xffff0000, v13
	v_and_b32_e32 v12, 0xffff0000, v12
	v_or_b32_sdwa v9, v13, v9 dst_sel:DWORD dst_unused:UNUSED_PAD src0_sel:DWORD src1_sel:WORD_1
	v_or_b32_sdwa v8, v12, v8 dst_sel:DWORD dst_unused:UNUSED_PAD src0_sel:DWORD src1_sel:WORD_1
	v_lshl_add_u64 v[12:13], v[0:1], 0, v[44:45]
	flat_store_dwordx2 v[12:13], v[8:9]
	v_pk_fma_f32 v[12:13], v[26:27], v[24:25], v[34:35]
	s_waitcnt vmcnt(0) lgkmcnt(0)
	v_lshlrev_b32_e32 v45, 16, v63
	v_pk_fma_f32 v[12:13], v[28:29], v[20:21], v[12:13]
	v_lshlrev_b32_e32 v44, 16, v62
	v_pk_fma_f32 v[12:13], v[30:31], v[58:59], v[12:13]
	v_pk_fma_f32 v[24:25], v[6:7], v[42:43], v[2:3]
	v_pk_fma_f32 v[12:13], v[36:37], v[44:45], v[12:13]
	v_pk_fma_f32 v[24:25], v[10:11], v[40:41], v[24:25]
	v_mul_f32_e32 v16, 0xbfb8aa3b, v12
	v_mul_f32_e32 v17, 0xbfb8aa3b, v13
	v_exp_f32_e32 v16, v16
	v_exp_f32_e32 v17, v17
	v_and_b32_e32 v9, 0xffff0000, v63
	v_and_b32_e32 v8, 0xffff0000, v62
	v_pk_fma_f32 v[24:25], v[18:19], v[48:49], v[24:25]
	v_pk_add_f32 v[16:17], v[16:17], 1.0 op_sel_hi:[1,0]
	v_pk_fma_f32 v[24:25], v[14:15], v[8:9], v[24:25]
	v_div_scale_f32 v32, s[6:7], v16, v16, v12
	v_rcp_f32_e32 v39, v32
	v_mul_f32_e32 v42, 0xbfb8aa3b, v24
	v_exp_f32_e32 v42, v42
	v_pk_fma_f32 v[40:41], v[6:7], v[40:41], v[2:3]
	v_fma_f32 v43, -v32, v39, 1.0
	v_fmac_f32_e32 v39, v43, v39
	v_div_scale_f32 v43, vcc, v12, v16, v12
	v_mul_f32_e32 v60, v43, v39
	v_fma_f32 v61, -v32, v60, v43
	v_fmac_f32_e32 v60, v61, v39
	v_div_scale_f32 v61, s[6:7], v17, v17, v13
	v_rcp_f32_e32 v62, v61
	v_fma_f32 v32, -v32, v60, v43
	v_div_fmas_f32 v32, v32, v39, v60
	v_mul_f32_e32 v39, 0xbfb8aa3b, v25
	v_exp_f32_e32 v43, v39
	v_div_fixup_f32 v12, v32, v16, v12
	v_fma_f32 v16, -v61, v62, 1.0
	v_fmac_f32_e32 v62, v16, v62
	v_div_scale_f32 v16, vcc, v13, v17, v13
	v_mul_f32_e32 v32, v16, v62
	v_fma_f32 v39, -v61, v32, v16
	v_pk_add_f32 v[42:43], v[42:43], 1.0 op_sel_hi:[1,0]
	v_fmac_f32_e32 v32, v39, v62
	v_div_scale_f32 v39, s[6:7], v42, v42, v24
	v_rcp_f32_e32 v60, v39
	v_fma_f32 v16, -v61, v32, v16
	v_div_fmas_f32 v16, v16, v62, v32
	v_div_fixup_f32 v13, v16, v17, v13
	v_fma_f32 v16, -v39, v60, 1.0
	v_fmac_f32_e32 v60, v16, v60
	v_div_scale_f32 v16, vcc, v24, v42, v24
	v_mul_f32_e32 v17, v16, v60
	v_fma_f32 v32, -v39, v17, v16
	v_fmac_f32_e32 v17, v32, v60
	v_div_scale_f32 v32, s[6:7], v43, v43, v25
	v_fma_f32 v16, -v39, v17, v16
	v_rcp_f32_e32 v39, v32
	v_div_fmas_f32 v16, v16, v60, v17
	v_div_fixup_f32 v16, v16, v42, v24
	v_pk_fma_f32 v[40:41], v[10:11], v[48:49], v[40:41]
	v_fma_f32 v17, -v32, v39, 1.0
	v_fmac_f32_e32 v39, v17, v39
	v_div_scale_f32 v17, vcc, v25, v43, v25
	v_mul_f32_e32 v24, v17, v39
	v_fma_f32 v42, -v32, v24, v17
	v_fmac_f32_e32 v24, v42, v39
	v_fma_f32 v17, -v32, v24, v17
	v_div_fmas_f32 v17, v17, v39, v24
	v_div_fixup_f32 v17, v17, v43, v25
	v_and_b32_sdwa v24, v13, v54 dst_sel:DWORD dst_unused:UNUSED_PAD src0_sel:WORD_1 src1_sel:DWORD
	v_and_b32_sdwa v25, v12, v54 dst_sel:DWORD dst_unused:UNUSED_PAD src0_sel:WORD_1 src1_sel:DWORD
	v_add3_u32 v12, v12, v25, s5
	v_add3_u32 v13, v13, v24, s5
	v_and_b32_sdwa v24, v17, v54 dst_sel:DWORD dst_unused:UNUSED_PAD src0_sel:WORD_1 src1_sel:DWORD
	v_and_b32_sdwa v25, v16, v54 dst_sel:DWORD dst_unused:UNUSED_PAD src0_sel:WORD_1 src1_sel:DWORD
	v_add3_u32 v17, v17, v24, s5
	v_add3_u32 v16, v16, v25, s5
	v_and_b32_e32 v17, 0xffff0000, v17
	v_and_b32_e32 v16, 0xffff0000, v16
	v_or_b32_sdwa v13, v17, v13 dst_sel:DWORD dst_unused:UNUSED_PAD src0_sel:DWORD src1_sel:WORD_1
	v_or_b32_sdwa v12, v16, v12 dst_sel:DWORD dst_unused:UNUSED_PAD src0_sel:DWORD src1_sel:WORD_1
	v_lshl_add_u64 v[16:17], v[0:1], 0, v[56:57]
	flat_store_dwordx2 v[16:17], v[12:13]
	v_pk_fma_f32 v[16:17], v[26:27], v[20:21], v[34:35]
	v_lshlrev_b32_e32 v25, 16, v65
	v_pk_fma_f32 v[16:17], v[28:29], v[58:59], v[16:17]
	v_lshlrev_b32_e32 v24, 16, v64
	v_pk_fma_f32 v[16:17], v[30:31], v[44:45], v[16:17]
	v_and_b32_e32 v13, 0xffff0000, v65
	v_pk_fma_f32 v[16:17], v[36:37], v[24:25], v[16:17]
	v_and_b32_e32 v12, 0xffff0000, v64
	v_mul_f32_e32 v20, 0xbfb8aa3b, v16
	v_mul_f32_e32 v21, 0xbfb8aa3b, v17
	v_exp_f32_e32 v20, v20
	v_exp_f32_e32 v21, v21
	v_pk_fma_f32 v[40:41], v[18:19], v[8:9], v[40:41]
	v_lshl_add_u64 v[4:5], v[0:1], 0, v[4:5]
	v_pk_fma_f32 v[40:41], v[14:15], v[12:13], v[40:41]
	v_pk_add_f32 v[20:21], v[20:21], 1.0 op_sel_hi:[1,0]
	v_mul_f32_e32 v42, 0xbfb8aa3b, v40
	v_div_scale_f32 v32, s[6:7], v20, v20, v16
	v_rcp_f32_e32 v39, v32
	v_exp_f32_e32 v42, v42
	v_fma_f32 v43, -v32, v39, 1.0
	v_fmac_f32_e32 v39, v43, v39
	v_div_scale_f32 v43, vcc, v16, v20, v16
	v_mul_f32_e32 v56, v43, v39
	v_fma_f32 v57, -v32, v56, v43
	v_fmac_f32_e32 v56, v57, v39
	v_div_scale_f32 v57, s[6:7], v21, v21, v17
	v_rcp_f32_e32 v60, v57
	v_fma_f32 v32, -v32, v56, v43
	v_div_fmas_f32 v32, v32, v39, v56
	v_mul_f32_e32 v39, 0xbfb8aa3b, v41
	v_exp_f32_e32 v43, v39
	v_div_fixup_f32 v16, v32, v20, v16
	v_fma_f32 v20, -v57, v60, 1.0
	v_fmac_f32_e32 v60, v20, v60
	v_div_scale_f32 v20, vcc, v17, v21, v17
	v_mul_f32_e32 v32, v20, v60
	v_fma_f32 v39, -v57, v32, v20
	v_pk_add_f32 v[42:43], v[42:43], 1.0 op_sel_hi:[1,0]
	v_fmac_f32_e32 v32, v39, v60
	v_div_scale_f32 v39, s[6:7], v42, v42, v40
	v_rcp_f32_e32 v56, v39
	v_fma_f32 v20, -v57, v32, v20
	v_div_fmas_f32 v20, v20, v60, v32
	v_div_fixup_f32 v17, v20, v21, v17
	v_fma_f32 v20, -v39, v56, 1.0
	v_fmac_f32_e32 v56, v20, v56
	v_div_scale_f32 v20, vcc, v40, v42, v40
	v_mul_f32_e32 v21, v20, v56
	v_fma_f32 v32, -v39, v21, v20
	v_fmac_f32_e32 v21, v32, v56
	v_div_scale_f32 v32, s[6:7], v43, v43, v41
	v_fma_f32 v20, -v39, v21, v20
	v_rcp_f32_e32 v39, v32
	v_div_fmas_f32 v20, v20, v56, v21
	v_div_fixup_f32 v20, v20, v42, v40
	v_fma_f32 v21, -v32, v39, 1.0
	v_fmac_f32_e32 v39, v21, v39
	v_div_scale_f32 v21, vcc, v41, v43, v41
	v_mul_f32_e32 v40, v21, v39
	v_fma_f32 v42, -v32, v40, v21
	v_fmac_f32_e32 v40, v42, v39
	v_fma_f32 v21, -v32, v40, v21
	v_div_fmas_f32 v21, v21, v39, v40
	v_div_fixup_f32 v21, v21, v43, v41
	v_and_b32_sdwa v32, v17, v54 dst_sel:DWORD dst_unused:UNUSED_PAD src0_sel:WORD_1 src1_sel:DWORD
	v_and_b32_sdwa v39, v16, v54 dst_sel:DWORD dst_unused:UNUSED_PAD src0_sel:WORD_1 src1_sel:DWORD
	v_add3_u32 v16, v16, v39, s5
	v_add3_u32 v17, v17, v32, s5
	v_and_b32_sdwa v32, v21, v54 dst_sel:DWORD dst_unused:UNUSED_PAD src0_sel:WORD_1 src1_sel:DWORD
	v_and_b32_sdwa v39, v20, v54 dst_sel:DWORD dst_unused:UNUSED_PAD src0_sel:WORD_1 src1_sel:DWORD
	v_add3_u32 v21, v21, v32, s5
	v_add3_u32 v20, v20, v39, s5
	v_and_b32_e32 v21, 0xffff0000, v21
	v_and_b32_e32 v20, 0xffff0000, v20
	v_or_b32_sdwa v17, v21, v17 dst_sel:DWORD dst_unused:UNUSED_PAD src0_sel:DWORD src1_sel:WORD_1
	v_or_b32_sdwa v16, v20, v16 dst_sel:DWORD dst_unused:UNUSED_PAD src0_sel:DWORD src1_sel:WORD_1
	v_pk_fma_f32 v[20:21], v[26:27], v[58:59], v[34:35]
	flat_store_dwordx2 v[4:5], v[16:17]
	v_pk_fma_f32 v[20:21], v[28:29], v[44:45], v[20:21]
	v_lshlrev_b32_e32 v17, 16, v51
	v_lshlrev_b32_e32 v16, 16, v50
	v_pk_fma_f32 v[20:21], v[30:31], v[24:25], v[20:21]
	v_pk_fma_f32 v[42:43], v[6:7], v[48:49], v[2:3]
	v_pk_fma_f32 v[40:41], v[36:37], v[16:17], v[20:21]
	v_pk_fma_f32 v[42:43], v[10:11], v[8:9], v[42:43]
	v_mul_f32_e32 v20, 0xbfb8aa3b, v40
	v_mul_f32_e32 v21, 0xbfb8aa3b, v41
	v_exp_f32_e32 v20, v20
	v_exp_f32_e32 v21, v21
	v_and_b32_e32 v5, 0xffff0000, v51
	v_and_b32_e32 v4, 0xffff0000, v50
	v_pk_fma_f32 v[42:43], v[18:19], v[12:13], v[42:43]
	v_pk_add_f32 v[50:51], v[20:21], 1.0 op_sel_hi:[1,0]
	v_pk_fma_f32 v[42:43], v[14:15], v[4:5], v[42:43]
	v_div_scale_f32 v32, s[6:7], v50, v50, v40
	v_mul_f32_e32 v20, 0xbfb8aa3b, v42
	v_exp_f32_e32 v56, v20
	v_or_b32_e32 v20, 4, v38
	v_ashrrev_i32_e32 v21, 31, v20
	v_lshlrev_b64 v[20:21], 12, v[20:21]
	v_lshl_add_u64 v[48:49], v[22:23], 0, v[20:21]
	v_mov_b64_e32 v[48:49], v[90:91]
	v_rcp_f32_e32 v39, v32
	v_pk_fma_f32 v[44:45], v[26:27], v[44:45], v[34:35]
	v_pk_fma_f32 v[8:9], v[6:7], v[8:9], v[2:3]
	v_pk_fma_f32 v[44:45], v[28:29], v[24:25], v[44:45]
	v_fma_f32 v57, -v32, v39, 1.0
	v_fmac_f32_e32 v39, v57, v39
	v_div_scale_f32 v57, vcc, v40, v50, v40
	v_mul_f32_e32 v58, v57, v39
	v_fma_f32 v59, -v32, v58, v57
	v_fmac_f32_e32 v58, v59, v39
	v_div_scale_f32 v59, s[6:7], v51, v51, v41
	v_fma_f32 v32, -v32, v58, v57
	v_rcp_f32_e32 v60, v59
	v_div_fmas_f32 v32, v32, v39, v58
	v_div_fixup_f32 v32, v32, v50, v40
	v_mul_f32_e32 v50, 0xbfb8aa3b, v43
	v_exp_f32_e32 v57, v50
	v_fma_f32 v39, -v59, v60, 1.0
	v_fmac_f32_e32 v60, v39, v60
	v_div_scale_f32 v39, vcc, v41, v51, v41
	v_mul_f32_e32 v40, v39, v60
	v_fma_f32 v50, -v59, v40, v39
	v_pk_add_f32 v[56:57], v[56:57], 1.0 op_sel_hi:[1,0]
	v_fmac_f32_e32 v40, v50, v60
	v_div_scale_f32 v50, s[6:7], v56, v56, v42
	v_rcp_f32_e32 v58, v50
	v_fma_f32 v39, -v59, v40, v39
	v_div_fmas_f32 v39, v39, v60, v40
	v_div_fixup_f32 v39, v39, v51, v41
	v_fma_f32 v40, -v50, v58, 1.0
	v_fmac_f32_e32 v58, v40, v58
	v_div_scale_f32 v40, vcc, v42, v56, v42
	v_mul_f32_e32 v41, v40, v58
	v_fma_f32 v51, -v50, v41, v40
	v_fmac_f32_e32 v41, v51, v58
	v_fma_f32 v40, -v50, v41, v40
	v_div_scale_f32 v50, s[6:7], v57, v57, v43
	v_rcp_f32_e32 v51, v50
	v_div_fmas_f32 v40, v40, v58, v41
	v_div_fixup_f32 v40, v40, v56, v42
	v_pk_fma_f32 v[44:45], v[30:31], v[16:17], v[44:45]
	v_fma_f32 v41, -v50, v51, 1.0
	v_fmac_f32_e32 v51, v41, v51
	v_div_scale_f32 v41, vcc, v43, v57, v43
	v_mul_f32_e32 v42, v41, v51
	v_fma_f32 v56, -v50, v42, v41
	v_fmac_f32_e32 v42, v56, v51
	v_fma_f32 v41, -v50, v42, v41
	v_div_fmas_f32 v41, v41, v51, v42
	v_div_fixup_f32 v41, v41, v57, v43
	v_and_b32_sdwa v42, v39, v54 dst_sel:DWORD dst_unused:UNUSED_PAD src0_sel:WORD_1 src1_sel:DWORD
	v_and_b32_sdwa v43, v32, v54 dst_sel:DWORD dst_unused:UNUSED_PAD src0_sel:WORD_1 src1_sel:DWORD
	v_add3_u32 v32, v32, v43, s5
	v_add3_u32 v39, v39, v42, s5
	v_and_b32_sdwa v42, v41, v54 dst_sel:DWORD dst_unused:UNUSED_PAD src0_sel:WORD_1 src1_sel:DWORD
	v_and_b32_sdwa v43, v40, v54 dst_sel:DWORD dst_unused:UNUSED_PAD src0_sel:WORD_1 src1_sel:DWORD
	v_add3_u32 v41, v41, v42, s5
	v_add3_u32 v40, v40, v43, s5
	v_and_b32_e32 v41, 0xffff0000, v41
	v_and_b32_e32 v40, 0xffff0000, v40
	v_or_b32_sdwa v41, v41, v39 dst_sel:DWORD dst_unused:UNUSED_PAD src0_sel:DWORD src1_sel:WORD_1
	v_or_b32_sdwa v40, v40, v32 dst_sel:DWORD dst_unused:UNUSED_PAD src0_sel:DWORD src1_sel:WORD_1
	v_lshl_add_u64 v[42:43], v[0:1], 0, v[46:47]
	flat_store_dwordx2 v[42:43], v[40:41]
	v_or_b32_e32 v40, 5, v38
	v_ashrrev_i32_e32 v41, 31, v40
	v_or_b32_e32 v38, 6, v38
	v_lshlrev_b64 v[46:47], 12, v[40:41]
	v_ashrrev_i32_e32 v39, 31, v38
	v_lshl_add_u64 v[40:41], v[22:23], 0, v[46:47]
	v_lshlrev_b64 v[42:43], 12, v[38:39]
	v_lshl_add_u64 v[38:39], v[22:23], 0, v[42:43]
	v_mov_b64_e32 v[50:51], v[92:93]
	v_mov_b64_e32 v[56:57], v[94:95]
	s_waitcnt vmcnt(0) lgkmcnt(0)
	v_lshlrev_b32_e32 v41, 16, v49
	v_lshlrev_b32_e32 v40, 16, v48
	v_pk_fma_f32 v[44:45], v[36:37], v[40:41], v[44:45]
	v_and_b32_e32 v38, 0xffff0000, v48
	v_mul_f32_e32 v32, 0xbfb8aa3b, v44
	v_exp_f32_e32 v48, v32
	v_mul_f32_e32 v32, 0xbfb8aa3b, v45
	v_and_b32_e32 v39, 0xffff0000, v49
	v_exp_f32_e32 v49, v32
	v_pk_fma_f32 v[8:9], v[10:11], v[12:13], v[8:9]
	v_pk_fma_f32 v[24:25], v[26:27], v[24:25], v[34:35]
	v_pk_fma_f32 v[8:9], v[18:19], v[4:5], v[8:9]
	v_pk_add_f32 v[48:49], v[48:49], 1.0 op_sel_hi:[1,0]
	v_pk_fma_f32 v[8:9], v[14:15], v[38:39], v[8:9]
	v_div_scale_f32 v32, s[6:7], v48, v48, v44
	v_rcp_f32_e32 v59, v32
	v_mul_f32_e32 v58, 0xbfb8aa3b, v8
	v_exp_f32_e32 v58, v58
	v_lshl_add_u64 v[20:21], v[0:1], 0, v[20:21]
	v_fma_f32 v60, -v32, v59, 1.0
	v_fmac_f32_e32 v59, v60, v59
	v_div_scale_f32 v60, vcc, v44, v48, v44
	v_mul_f32_e32 v61, v60, v59
	v_fma_f32 v62, -v32, v61, v60
	v_fmac_f32_e32 v61, v62, v59
	v_fma_f32 v32, -v32, v61, v60
	v_div_scale_f32 v60, s[6:7], v49, v49, v45
	v_rcp_f32_e32 v62, v60
	v_div_fmas_f32 v32, v32, v59, v61
	v_mul_f32_e32 v59, 0xbfb8aa3b, v9
	v_div_fixup_f32 v32, v32, v48, v44
	v_fma_f32 v44, -v60, v62, 1.0
	v_exp_f32_e32 v59, v59
	v_fmac_f32_e32 v62, v44, v62
	v_div_scale_f32 v44, vcc, v45, v49, v45
	v_mul_f32_e32 v48, v44, v62
	v_fma_f32 v61, -v60, v48, v44
	v_fmac_f32_e32 v48, v61, v62
	v_pk_add_f32 v[58:59], v[58:59], 1.0 op_sel_hi:[1,0]
	v_fma_f32 v44, -v60, v48, v44
	v_div_scale_f32 v60, s[6:7], v58, v58, v8
	v_rcp_f32_e32 v61, v60
	v_div_fmas_f32 v44, v44, v62, v48
	v_div_fixup_f32 v44, v44, v49, v45
	v_pk_fma_f32 v[24:25], v[28:29], v[16:17], v[24:25]
	v_fma_f32 v45, -v60, v61, 1.0
	v_fmac_f32_e32 v61, v45, v61
	v_div_scale_f32 v45, vcc, v8, v58, v8
	v_mul_f32_e32 v48, v45, v61
	v_fma_f32 v49, -v60, v48, v45
	v_fmac_f32_e32 v48, v49, v61
	v_div_scale_f32 v49, s[6:7], v59, v59, v9
	v_fma_f32 v45, -v60, v48, v45
	v_rcp_f32_e32 v60, v49
	v_div_fmas_f32 v45, v45, v61, v48
	v_div_fixup_f32 v8, v45, v58, v8
	v_pk_fma_f32 v[24:25], v[30:31], v[40:41], v[24:25]
	v_fma_f32 v45, -v49, v60, 1.0
	v_fmac_f32_e32 v60, v45, v60
	v_div_scale_f32 v45, vcc, v9, v59, v9
	v_mul_f32_e32 v48, v45, v60
	v_fma_f32 v58, -v49, v48, v45
	v_fmac_f32_e32 v48, v58, v60
	v_fma_f32 v45, -v49, v48, v45
	v_div_fmas_f32 v45, v45, v60, v48
	v_div_fixup_f32 v9, v45, v59, v9
	v_and_b32_sdwa v45, v44, v54 dst_sel:DWORD dst_unused:UNUSED_PAD src0_sel:WORD_1 src1_sel:DWORD
	v_and_b32_sdwa v48, v32, v54 dst_sel:DWORD dst_unused:UNUSED_PAD src0_sel:WORD_1 src1_sel:DWORD
	v_add3_u32 v32, v32, v48, s5
	v_add3_u32 v44, v44, v45, s5
	v_and_b32_sdwa v45, v9, v54 dst_sel:DWORD dst_unused:UNUSED_PAD src0_sel:WORD_1 src1_sel:DWORD
	v_and_b32_sdwa v48, v8, v54 dst_sel:DWORD dst_unused:UNUSED_PAD src0_sel:WORD_1 src1_sel:DWORD
	v_add3_u32 v9, v9, v45, s5
	v_add3_u32 v8, v8, v48, s5
	v_and_b32_e32 v9, 0xffff0000, v9
	v_and_b32_e32 v8, 0xffff0000, v8
	v_or_b32_sdwa v9, v9, v44 dst_sel:DWORD dst_unused:UNUSED_PAD src0_sel:DWORD src1_sel:WORD_1
	v_or_b32_sdwa v8, v8, v32 dst_sel:DWORD dst_unused:UNUSED_PAD src0_sel:DWORD src1_sel:WORD_1
	flat_store_dwordx2 v[20:21], v[8:9]
	v_lshlrev_b32_e32 v9, 16, v51
	v_lshlrev_b32_e32 v8, 16, v50
	v_pk_fma_f32 v[24:25], v[36:37], v[8:9], v[24:25]
	v_and_b32_e32 v20, 0xffff0000, v50
	v_mul_f32_e32 v32, 0xbfb8aa3b, v24
	v_exp_f32_e32 v44, v32
	v_mul_f32_e32 v32, 0xbfb8aa3b, v25
	v_exp_f32_e32 v45, v32
	v_and_b32_e32 v21, 0xffff0000, v51
	v_pk_fma_f32 v[12:13], v[6:7], v[12:13], v[2:3]
	v_pk_fma_f32 v[16:17], v[26:27], v[16:17], v[34:35]
	v_pk_add_f32 v[44:45], v[44:45], 1.0 op_sel_hi:[1,0]
	v_pk_fma_f32 v[12:13], v[10:11], v[4:5], v[12:13]
	v_div_scale_f32 v32, s[6:7], v44, v44, v24
	v_rcp_f32_e32 v49, v32
	v_pk_fma_f32 v[12:13], v[18:19], v[38:39], v[12:13]
	v_pk_fma_f32 v[16:17], v[28:29], v[40:41], v[16:17]
	v_pk_fma_f32 v[12:13], v[14:15], v[20:21], v[12:13]
	v_fma_f32 v50, -v32, v49, 1.0
	v_fmac_f32_e32 v49, v50, v49
	v_div_scale_f32 v50, vcc, v24, v44, v24
	v_mul_f32_e32 v51, v50, v49
	v_fma_f32 v58, -v32, v51, v50
	v_fmac_f32_e32 v51, v58, v49
	v_fma_f32 v32, -v32, v51, v50
	v_div_scale_f32 v50, s[6:7], v45, v45, v25
	v_rcp_f32_e32 v58, v50
	v_mul_f32_e32 v48, 0xbfb8aa3b, v12
	v_div_fmas_f32 v32, v32, v49, v51
	v_mul_f32_e32 v49, 0xbfb8aa3b, v13
	v_exp_f32_e32 v48, v48
	v_div_fixup_f32 v24, v32, v44, v24
	v_fma_f32 v32, -v50, v58, 1.0
	v_exp_f32_e32 v49, v49
	v_fmac_f32_e32 v58, v32, v58
	v_div_scale_f32 v32, vcc, v25, v45, v25
	v_mul_f32_e32 v44, v32, v58
	v_fma_f32 v51, -v50, v44, v32
	v_fmac_f32_e32 v44, v51, v58
	v_pk_add_f32 v[48:49], v[48:49], 1.0 op_sel_hi:[1,0]
	v_fma_f32 v32, -v50, v44, v32
	v_div_scale_f32 v50, s[6:7], v48, v48, v12
	v_rcp_f32_e32 v51, v50
	v_div_fmas_f32 v32, v32, v58, v44
	v_div_fixup_f32 v25, v32, v45, v25
	v_pk_fma_f32 v[16:17], v[30:31], v[8:9], v[16:17]
	v_fma_f32 v32, -v50, v51, 1.0
	v_fmac_f32_e32 v51, v32, v51
	v_div_scale_f32 v32, vcc, v12, v48, v12
	v_mul_f32_e32 v44, v32, v51
	v_fma_f32 v45, -v50, v44, v32
	v_fmac_f32_e32 v44, v45, v51
	v_div_scale_f32 v45, s[6:7], v49, v49, v13
	v_fma_f32 v32, -v50, v44, v32
	v_rcp_f32_e32 v50, v45
	v_div_fmas_f32 v32, v32, v51, v44
	v_div_fixup_f32 v12, v32, v48, v12
	v_pk_fma_f32 v[4:5], v[6:7], v[4:5], v[2:3]
	v_fma_f32 v32, -v45, v50, 1.0
	v_fmac_f32_e32 v50, v32, v50
	v_div_scale_f32 v32, vcc, v13, v49, v13
	v_mul_f32_e32 v44, v32, v50
	v_fma_f32 v48, -v45, v44, v32
	v_fmac_f32_e32 v44, v48, v50
	v_fma_f32 v32, -v45, v44, v32
	v_div_fmas_f32 v32, v32, v50, v44
	v_div_fixup_f32 v13, v32, v49, v13
	v_and_b32_sdwa v32, v25, v54 dst_sel:DWORD dst_unused:UNUSED_PAD src0_sel:WORD_1 src1_sel:DWORD
	v_and_b32_sdwa v44, v24, v54 dst_sel:DWORD dst_unused:UNUSED_PAD src0_sel:WORD_1 src1_sel:DWORD
	v_add3_u32 v24, v24, v44, s5
	v_add3_u32 v25, v25, v32, s5
	v_and_b32_sdwa v32, v13, v54 dst_sel:DWORD dst_unused:UNUSED_PAD src0_sel:WORD_1 src1_sel:DWORD
	v_and_b32_sdwa v44, v12, v54 dst_sel:DWORD dst_unused:UNUSED_PAD src0_sel:WORD_1 src1_sel:DWORD
	v_add3_u32 v13, v13, v32, s5
	v_add3_u32 v12, v12, v44, s5
	v_and_b32_e32 v13, 0xffff0000, v13
	v_and_b32_e32 v12, 0xffff0000, v12
	v_or_b32_sdwa v13, v13, v25 dst_sel:DWORD dst_unused:UNUSED_PAD src0_sel:DWORD src1_sel:WORD_1
	v_or_b32_sdwa v12, v12, v24 dst_sel:DWORD dst_unused:UNUSED_PAD src0_sel:DWORD src1_sel:WORD_1
	v_lshl_add_u64 v[24:25], v[0:1], 0, v[46:47]
	flat_store_dwordx2 v[24:25], v[12:13]
	v_lshlrev_b32_e32 v13, 16, v57
	v_lshlrev_b32_e32 v12, 16, v56
	v_pk_fma_f32 v[16:17], v[36:37], v[12:13], v[16:17]
	v_pk_fma_f32 v[4:5], v[10:11], v[38:39], v[4:5]
	v_mul_f32_e32 v32, 0xbfb8aa3b, v16
	v_exp_f32_e32 v44, v32
	v_mul_f32_e32 v32, 0xbfb8aa3b, v17
	v_exp_f32_e32 v45, v32
	v_and_b32_e32 v25, 0xffff0000, v57
	v_and_b32_e32 v24, 0xffff0000, v56
	v_pk_fma_f32 v[4:5], v[18:19], v[20:21], v[4:5]
	v_pk_add_f32 v[44:45], v[44:45], 1.0 op_sel_hi:[1,0]
	v_pk_fma_f32 v[4:5], v[14:15], v[24:25], v[4:5]
	v_div_scale_f32 v32, s[6:7], v44, v44, v16
	v_rcp_f32_e32 v47, v32
	v_mul_f32_e32 v46, 0xbfb8aa3b, v4
	v_exp_f32_e32 v46, v46
	v_pk_fma_f32 v[26:27], v[26:27], v[40:41], v[34:35]
	v_fma_f32 v48, -v32, v47, 1.0
	v_fmac_f32_e32 v47, v48, v47
	v_div_scale_f32 v48, vcc, v16, v44, v16
	v_mul_f32_e32 v49, v48, v47
	v_fma_f32 v50, -v32, v49, v48
	v_fmac_f32_e32 v49, v50, v47
	v_fma_f32 v32, -v32, v49, v48
	v_div_scale_f32 v48, s[6:7], v45, v45, v17
	v_rcp_f32_e32 v50, v48
	v_div_fmas_f32 v32, v32, v47, v49
	v_mul_f32_e32 v47, 0xbfb8aa3b, v5
	v_div_fixup_f32 v16, v32, v44, v16
	v_fma_f32 v32, -v48, v50, 1.0
	v_exp_f32_e32 v47, v47
	v_fmac_f32_e32 v50, v32, v50
	v_div_scale_f32 v32, vcc, v17, v45, v17
	v_mul_f32_e32 v44, v32, v50
	v_fma_f32 v49, -v48, v44, v32
	v_fmac_f32_e32 v44, v49, v50
	v_pk_add_f32 v[46:47], v[46:47], 1.0 op_sel_hi:[1,0]
	v_fma_f32 v32, -v48, v44, v32
	v_div_scale_f32 v48, s[6:7], v46, v46, v4
	v_rcp_f32_e32 v49, v48
	v_div_fmas_f32 v32, v32, v50, v44
	v_div_fixup_f32 v17, v32, v45, v17
	v_pk_fma_f32 v[8:9], v[28:29], v[8:9], v[26:27]
	v_fma_f32 v32, -v48, v49, 1.0
	v_fmac_f32_e32 v49, v32, v49
	v_div_scale_f32 v32, vcc, v4, v46, v4
	v_mul_f32_e32 v44, v32, v49
	v_fma_f32 v45, -v48, v44, v32
	v_fmac_f32_e32 v44, v45, v49
	v_div_scale_f32 v45, s[6:7], v47, v47, v5
	v_fma_f32 v32, -v48, v44, v32
	v_rcp_f32_e32 v48, v45
	v_div_fmas_f32 v32, v32, v49, v44
	v_div_fixup_f32 v4, v32, v46, v4
	v_pk_fma_f32 v[8:9], v[30:31], v[12:13], v[8:9]
	v_fma_f32 v32, -v45, v48, 1.0
	v_fmac_f32_e32 v48, v32, v48
	v_div_scale_f32 v32, vcc, v5, v47, v5
	v_mul_f32_e32 v44, v32, v48
	v_fma_f32 v46, -v45, v44, v32
	v_fmac_f32_e32 v44, v46, v48
	v_fma_f32 v32, -v45, v44, v32
	v_div_fmas_f32 v32, v32, v48, v44
	v_div_fixup_f32 v5, v32, v47, v5
	v_and_b32_sdwa v32, v17, v54 dst_sel:DWORD dst_unused:UNUSED_PAD src0_sel:WORD_1 src1_sel:DWORD
	v_and_b32_sdwa v44, v16, v54 dst_sel:DWORD dst_unused:UNUSED_PAD src0_sel:WORD_1 src1_sel:DWORD
	v_add3_u32 v16, v16, v44, s5
	v_add3_u32 v17, v17, v32, s5
	v_and_b32_sdwa v32, v5, v54 dst_sel:DWORD dst_unused:UNUSED_PAD src0_sel:WORD_1 src1_sel:DWORD
	v_and_b32_sdwa v44, v4, v54 dst_sel:DWORD dst_unused:UNUSED_PAD src0_sel:WORD_1 src1_sel:DWORD
	v_add3_u32 v5, v5, v32, s5
	v_add3_u32 v4, v4, v44, s5
	v_and_b32_e32 v5, 0xffff0000, v5
	v_and_b32_e32 v4, 0xffff0000, v4
	v_or_b32_sdwa v5, v5, v17 dst_sel:DWORD dst_unused:UNUSED_PAD src0_sel:DWORD src1_sel:WORD_1
	v_or_b32_sdwa v4, v4, v16 dst_sel:DWORD dst_unused:UNUSED_PAD src0_sel:DWORD src1_sel:WORD_1
	v_lshl_add_u64 v[16:17], v[0:1], 0, v[42:43]
	flat_store_dwordx2 v[16:17], v[4:5]
	v_or_b32_e32 v4, 7, v55
	v_ashrrev_i32_e32 v5, 31, v4
	v_lshlrev_b64 v[4:5], 12, v[4:5]
	v_lshl_add_u64 v[16:17], v[22:23], 0, v[4:5]
	v_mov_b64_e32 v[16:17], v[96:97]
	v_pk_fma_f32 v[2:3], v[6:7], v[38:39], v[2:3]
	v_lshl_add_u64 v[0:1], v[0:1], 0, v[4:5]
	v_pk_fma_f32 v[2:3], v[10:11], v[20:21], v[2:3]
	s_waitcnt vmcnt(0) lgkmcnt(0)
	v_lshlrev_b32_e32 v23, 16, v17
	v_lshlrev_b32_e32 v22, 16, v16
	v_pk_fma_f32 v[8:9], v[36:37], v[22:23], v[8:9]
	v_and_b32_e32 v17, 0xffff0000, v17
	v_mul_f32_e32 v12, 0xbfb8aa3b, v8
	v_mul_f32_e32 v13, 0xbfb8aa3b, v9
	v_exp_f32_e32 v12, v12
	v_exp_f32_e32 v13, v13
	v_and_b32_e32 v16, 0xffff0000, v16
	v_pk_fma_f32 v[2:3], v[18:19], v[24:25], v[2:3]
	v_pk_add_f32 v[6:7], v[12:13], 1.0 op_sel_hi:[1,0]
	s_nop 0
	v_div_scale_f32 v11, s[6:7], v6, v6, v8
	v_rcp_f32_e32 v12, v11
	v_pk_fma_f32 v[2:3], v[14:15], v[16:17], v[2:3]
	v_fma_f32 v13, -v11, v12, 1.0
	v_fmac_f32_e32 v12, v13, v12
	v_div_scale_f32 v13, vcc, v8, v6, v8
	v_mul_f32_e32 v14, v13, v12
	v_fma_f32 v15, -v11, v14, v13
	v_fmac_f32_e32 v14, v15, v12
	v_fma_f32 v11, -v11, v14, v13
	v_div_scale_f32 v13, s[6:7], v7, v7, v9
	v_rcp_f32_e32 v15, v13
	v_div_fmas_f32 v11, v11, v12, v14
	v_mul_f32_e32 v10, 0xbfb8aa3b, v2
	v_div_fixup_f32 v6, v11, v6, v8
	v_mul_f32_e32 v11, 0xbfb8aa3b, v3
	v_exp_f32_e32 v10, v10
	v_fma_f32 v8, -v13, v15, 1.0
	v_exp_f32_e32 v11, v11
	v_fmac_f32_e32 v15, v8, v15
	v_div_scale_f32 v8, vcc, v9, v7, v9
	v_mul_f32_e32 v12, v8, v15
	v_fma_f32 v14, -v13, v12, v8
	v_fmac_f32_e32 v12, v14, v15
	v_pk_add_f32 v[10:11], v[10:11], 1.0 op_sel_hi:[1,0]
	v_fma_f32 v8, -v13, v12, v8
	v_div_scale_f32 v13, s[6:7], v10, v10, v2
	v_rcp_f32_e32 v14, v13
	v_div_fmas_f32 v8, v8, v15, v12
	v_div_fixup_f32 v7, v8, v7, v9
	v_fma_f32 v8, -v13, v14, 1.0
	v_fmac_f32_e32 v14, v8, v14
	v_div_scale_f32 v8, vcc, v2, v10, v2
	v_mul_f32_e32 v9, v8, v14
	v_fma_f32 v12, -v13, v9, v8
	v_fmac_f32_e32 v9, v12, v14
	v_div_scale_f32 v12, s[6:7], v11, v11, v3
	v_fma_f32 v8, -v13, v9, v8
	v_rcp_f32_e32 v13, v12
	v_div_fmas_f32 v8, v8, v14, v9
	v_div_fixup_f32 v2, v8, v10, v2
	v_fma_f32 v8, -v12, v13, 1.0
	v_fmac_f32_e32 v13, v8, v13
	v_div_scale_f32 v8, vcc, v3, v11, v3
	v_mul_f32_e32 v9, v8, v13
	v_fma_f32 v10, -v12, v9, v8
	v_fmac_f32_e32 v9, v10, v13
	v_fma_f32 v8, -v12, v9, v8
	v_div_fmas_f32 v8, v8, v13, v9
	v_div_fixup_f32 v3, v8, v11, v3
	v_and_b32_sdwa v8, v7, v54 dst_sel:DWORD dst_unused:UNUSED_PAD src0_sel:WORD_1 src1_sel:DWORD
	v_and_b32_sdwa v9, v6, v54 dst_sel:DWORD dst_unused:UNUSED_PAD src0_sel:WORD_1 src1_sel:DWORD
	v_add3_u32 v6, v6, v9, s5
	v_add3_u32 v7, v7, v8, s5
	v_and_b32_sdwa v8, v3, v54 dst_sel:DWORD dst_unused:UNUSED_PAD src0_sel:WORD_1 src1_sel:DWORD
	v_and_b32_sdwa v9, v2, v54 dst_sel:DWORD dst_unused:UNUSED_PAD src0_sel:WORD_1 src1_sel:DWORD
	v_add3_u32 v3, v3, v8, s5
	v_add3_u32 v2, v2, v9, s5
	v_and_b32_e32 v3, 0xffff0000, v3
	v_and_b32_e32 v2, 0xffff0000, v2
	v_cmp_lt_i32_e32 vcc, s24, v52
	v_or_b32_sdwa v3, v3, v7 dst_sel:DWORD dst_unused:UNUSED_PAD src0_sel:DWORD src1_sel:WORD_1
	v_or_b32_sdwa v2, v2, v6 dst_sel:DWORD dst_unused:UNUSED_PAD src0_sel:DWORD src1_sel:WORD_1
	s_or_b64 s[22:23], vcc, s[22:23]
	flat_store_dwordx2 v[0:1], v[2:3]
	s_andn2_b64 exec, exec, s[22:23]
	s_cbranch_execz .LBB0_593

.LBB0_768:
	v_lshl_add_u64 v[38:39], v[0:1], 0, s[28:29]
	v_add_co_u32_e32 v66, vcc, 0x21752000, v38
	v_lshl_add_u64 v[42:43], v[22:23], 0, s[28:29]
	s_nop 0
	v_addc_co_u32_e32 v67, vcc, 0, v39, vcc
	v_add_co_u32_e32 v70, vcc, 0x25b52000, v42
	v_lshl_add_u64 v[50:51], v[20:21], 0, s[28:29]
	s_nop 0
	v_addc_co_u32_e32 v71, vcc, 0, v43, vcc
	v_add_co_u32_e32 v72, vcc, 0x25b52000, v50
	s_nop 0
	v_addc_co_u32_e32 v73, vcc, 0, v51, vcc
	s_nop 0
	global_load_dwordx4 v[76:79], v[66:67], off
	global_load_dwordx4 v[80:83], v[66:67], off offset:64
	global_load_dwordx4 v[84:87], v[70:71], off
	global_load_dwordx4 v[88:91], v[70:71], off offset:64
	global_load_dwordx4 v[92:95], v[72:73], off
	global_load_dwordx4 v[96:99], v[72:73], off offset:64
	global_load_dwordx4 v[100:103], v[66:67], off offset:128
	global_load_dwordx4 v[104:107], v[66:67], off offset:192
	global_load_dwordx4 v[108:111], v[66:67], off offset:256
	global_load_dwordx4 v[112:115], v[70:71], off offset:128
	global_load_dwordx4 v[116:119], v[70:71], off offset:192
	global_load_dwordx4 v[120:123], v[72:73], off offset:128
	global_load_dwordx4 v[124:127], v[72:73], off offset:192
	global_load_dwordx4 v[128:131], v[66:67], off offset:320
	global_load_dwordx4 v[132:135], v[66:67], off offset:384
	global_load_dwordx4 v[136:139], v[66:67], off offset:448
	global_load_dwordx4 v[140:143], v[70:71], off offset:256
	global_load_dwordx4 v[144:147], v[70:71], off offset:320
	global_load_dwordx4 v[148:151], v[72:73], off offset:256
	global_load_dwordx4 v[152:155], v[72:73], off offset:320
	global_load_dwordx4 v[156:159], v[70:71], off offset:384
	global_load_dwordx4 v[160:163], v[72:73], off offset:384
	global_load_dwordx4 v[164:167], v[70:71], off offset:448
	global_load_dwordx4 v[168:171], v[72:73], off offset:448
	s_add_u32 s28, s28, 0x200
	s_addc_u32 s29, s29, 0
	s_waitcnt vmcnt(0)
	v_mfma_f32_16x16x32_bf16 v[4:7], v[76:79], v[84:87], v[4:7]
	v_mfma_f32_16x16x32_bf16 v[8:11], v[76:79], v[92:95], v[8:11]
	v_mfma_f32_16x16x32_bf16 v[4:7], v[80:83], v[88:91], v[4:7]
	v_mfma_f32_16x16x32_bf16 v[8:11], v[80:83], v[96:99], v[8:11]
	v_mfma_f32_16x16x32_bf16 v[4:7], v[100:103], v[112:115], v[4:7]
	v_mfma_f32_16x16x32_bf16 v[4:7], v[104:107], v[116:119], v[4:7]
	v_mfma_f32_16x16x32_bf16 v[8:11], v[100:103], v[120:123], v[8:11]
	v_mfma_f32_16x16x32_bf16 v[8:11], v[104:107], v[124:127], v[8:11]
	v_mfma_f32_16x16x32_bf16 v[4:7], v[108:111], v[140:143], v[4:7]
	v_mfma_f32_16x16x32_bf16 v[8:11], v[108:111], v[148:151], v[8:11]
	v_mfma_f32_16x16x32_bf16 v[4:7], v[128:131], v[144:147], v[4:7]
	v_mfma_f32_16x16x32_bf16 v[8:11], v[128:131], v[152:155], v[8:11]
	v_mfma_f32_16x16x32_bf16 v[4:7], v[132:135], v[156:159], v[4:7]
	v_mfma_f32_16x16x32_bf16 v[8:11], v[132:135], v[160:163], v[8:11]
	v_mfma_f32_16x16x32_bf16 v[4:7], v[136:139], v[164:167], v[4:7]
	v_mfma_f32_16x16x32_bf16 v[8:11], v[136:139], v[168:171], v[8:11]
	s_cmpk_eq_i32 s28, 0x400
	s_cbranch_scc0 .LBB0_768
	s_ashr_i32 s27, s26, 31
	s_lshl_b64 s[28:29], s[26:27], 14
	v_lshl_add_u64 v[0:1], s[28:29], 0, v[16:17]
	s_add_i32 s26, s26, s52
	s_add_i32 s0, s0, s1
	s_add_i32 s4, s4, s5
	v_lshl_add_u64 v[0:1], v[14:15], 0, v[0:1]
	s_cmpk_gt_i32 s26, 0x3ff
	flat_store_dword v[0:1], v4
	flat_store_dword v[0:1], v5 offset:256
	flat_store_dword v[0:1], v6 offset:512
	flat_store_dword v[0:1], v7 offset:768
	flat_store_dword v[0:1], v8 offset:64
	flat_store_dword v[0:1], v9 offset:320
	flat_store_dword v[0:1], v10 offset:576
	flat_store_dword v[0:1], v11 offset:832
	s_cbranch_scc0 .LBB0_765
